# P3: A-fragment VGPR tuples shifted by 2 as well (src0 and src1 of the MFMAs start on different banks)
# baseline (speedup 1.0000x reference)
; #define PG8_LAS __attribute__((address_space(3)))
; template <class Epi, class Sched, bool ALIGN_EPI = false, bool SP2 = false, bool RS = false, bool BPRE = false>
; __device__ __forceinline__ void gemm_phase(PG8_LAS unsigned char* lds, const Gemm g, const Sched& S, const Epi& E, const float* rs_ss = nullptr, PG8_LAS float* rs_tab = nullptr) {
;     ...
;         const bool has_next = S.next(ui + 1, nxt);
;         const char* nA = has_next ? (const char*)g.A + (size_t)nxt.pm * tstep : cA; const char* nB = has_next ? (const char*)g.Bt + (size_t)nxt.pn * tstep : cB;
;         for (int t = 0; t < nt; t += 2) {
;             const bool last = (t == nt - 2);
;             if constexpr (RS) { if (t == 16 || t == 32) { const PG8_LAS float* tp = rs_tab + (ui & 1) * 768 + (t == 32 ? 256 : 0);
;                 _Pragma("unroll") for (int a = 0; a < 2; ++a) _Pragma("unroll") for (int m = 0; m < 4; ++m) { const float f = tp[a * HALF + wr * 64 + m * 16 + fr];
;                     _Pragma("unroll") for (int b = 0; b < 2; ++b) _Pragma("unroll") for (int n = 0; n < 2; ++n) acc[a][b][m][n] = acc[a][b][m][n] * f; } } }
;             const char* a1 = cA + (size_t)(t + 1) * kstep;
;             const char* a2 = last ? nA : cA + (size_t)(t + 2) * kstep; const char* b2 = last ? nB : cB + (size_t)(t + 2) * kstep;
;             const char* a3 = a2 + kstep; const char* b3 = b2 + kstep;
;             if (last && has_next) S.a_ready(nxt);
;             if constexpr (SP2) {
;             PG8_LDB(B0, 0, 0); PG8_LDB(B1, 0, 1); PG8_SCHED; PG8_LDA(At, 0, 0); PG8_STAGE(PG8_SA(1, 1), a1 + hstep, voffA);
;             PG8_WAIT_V(8); PG8_WAIT_L(0); PG8_BAR; PG8_MMA(0, 0, At, B0); PG8_MMA(0, 1, At, B1); PG8_BAR; PG8_SCHED;
;             PG8_LDA(At, 0, 1); PG8_STAGE(PG8_SB(0, 0), b2, voffB); PG8_STAGE(PG8_SB(0, 1), b2 + hstep, voffB); PG8_STAGE(PG8_SA(0, 0), a2, voffA);
;             PG8_WAIT_V(8); PG8_WAIT_L(0); PG8_BAR; PG8_MMA(1, 0, At, B0); PG8_MMA(1, 1, At, B1); PG8_BAR; PG8_SCHED;
;             PG8_LDB(B0, 1, 0); PG8_LDB(B1, 1, 1); PG8_SCHED; PG8_LDA(At, 1, 0); PG8_STAGE(PG8_SA(0, 1), a2 + hstep, voffA);
;             PG8_WAIT_V(8); PG8_WAIT_L(0); PG8_BAR; PG8_MMA(0, 0, At, B0); PG8_MMA(0, 1, At, B1); PG8_BAR; PG8_SCHED;
;             PG8_LDA(At, 1, 1); PG8_STAGE(PG8_SB(1, 0), b3, voffB); PG8_STAGE(PG8_SB(1, 1), b3 + hstep, voffB); PG8_STAGE(PG8_SA(1, 0), a3, voffA);
.LBB0_751:
	s_bitcmp1_b32 s40, 0
	v_mov_b32_e32 v4, v2
	v_mov_b32_e32 v5, v2
	s_cselect_b32 s6, 0xc00, 0
	s_add_u32 s71, s38, 0x8000
	v_mov_b32_e32 v3, v2
	s_waitcnt lgkmcnt(0)
	s_waitcnt vmcnt(0)
	s_mov_b32 s73, 0
	v_add_u32_e32 v158, s6, v151
	v_lshl_add_u64 v[146:147], s[10:11], 0, v[138:139]
	v_lshl_add_u64 v[148:149], s[10:11], 0, v[140:141]
	s_addc_u32 s72, s39, 0
	s_mov_b64 s[6:7], 0
	s_add_u32 s38, s10, s6
	v_add_u32_e32 v3, s64, v150
	s_addc_u32 s39, s11, s7
	ds_read_b128 v[160:163], v3
	ds_read_b128 v[164:167], v3 offset:1024
	ds_read_b128 v[168:171], v3 offset:2048
	ds_read_b128 v[172:175], v3 offset:3072
	v_add_u32_e32 v3, s65, v150
	s_add_u32 s38, s38, 0x8000
	ds_read_b128 v[176:179], v3
	ds_read_b128 v[180:183], v3 offset:1024
	ds_read_b128 v[184:187], v3 offset:2048
	ds_read_b128 v[188:191], v3 offset:3072
	s_addc_u32 s39, s39, 0
	s_add_u32 s40, s71, s6
	s_addc_u32 s41, s72, s7
	s_cmp_eq_u32 s6, 0xb8000
	s_cselect_b32 s42, s20, s38
	s_cselect_b32 s43, s21, s39
	s_cselect_b32 s40, s36, s40
	s_cselect_b32 s41, s37, s41
	s_add_u32 s38, s42, 0x4000
	s_addc_u32 s39, s43, 0
	v_lshl_add_u64 v[4:5], v[146:147], 0, s[6:7]
	s_add_i32 m0, s55, 0xc000
	ds_read_b128 v[194:197], v154
	ds_read_b128 v[198:201], v154 offset:1024
	ds_read_b128 v[202:205], v154 offset:2048
	ds_read_b128 v[206:209], v154 offset:3072
	ds_read_b128 v[210:213], v154 offset:4096
	ds_read_b128 v[214:217], v154 offset:5120
	ds_read_b128 v[218:221], v154 offset:6144
	ds_read_b128 v[222:225], v154 offset:7168
	global_load_lds_dwordx4 v[4:5], off
	v_lshl_add_u64 v[4:5], v[148:149], 0, s[6:7]
	s_add_i32 m0, s55, 0xe000
	s_nop 0
	global_load_lds_dwordx4 v[4:5], off
	s_waitcnt vmcnt(8)
	s_waitcnt lgkmcnt(0)
	s_barrier
	s_setprio 1
	s_waitcnt lgkmcnt(0)
	v_mfma_f32_16x16x32_bf16 v[130:133], v[160:163], v[194:197], 0
	v_mfma_f32_16x16x32_bf16 v[130:133], v[164:167], v[198:201], v[130:133]
	v_mfma_f32_16x16x32_bf16 v[126:129], v[172:175], v[198:201], 0
	v_mfma_f32_16x16x32_bf16 v[126:129], v[168:171], v[194:197], v[126:129]
	v_mfma_f32_16x16x32_bf16 v[110:113], v[168:171], v[202:205], 0
	v_mfma_f32_16x16x32_bf16 v[110:113], v[172:175], v[206:209], v[110:113]
	v_mfma_f32_16x16x32_bf16 v[114:117], v[164:167], v[206:209], 0
	v_mfma_f32_16x16x32_bf16 v[114:117], v[160:163], v[202:205], v[114:117]
	v_mfma_f32_16x16x32_bf16 v[98:101], v[160:163], v[210:213], 0
	v_mfma_f32_16x16x32_bf16 v[98:101], v[164:167], v[214:217], v[98:101]
	v_mfma_f32_16x16x32_bf16 v[94:97], v[172:175], v[214:217], 0
	v_mfma_f32_16x16x32_bf16 v[94:97], v[168:171], v[210:213], v[94:97]
	v_mfma_f32_16x16x32_bf16 v[78:81], v[168:171], v[218:221], 0
	v_mfma_f32_16x16x32_bf16 v[78:81], v[172:175], v[222:225], v[78:81]
	v_mfma_f32_16x16x32_bf16 v[82:85], v[164:167], v[222:225], 0
	v_mfma_f32_16x16x32_bf16 v[82:85], v[160:163], v[218:221], v[82:85]
	s_setprio 0
	s_setprio 1
	v_mfma_f32_16x16x32_bf16 v[74:77], v[176:179], v[218:221], 0
	v_mfma_f32_16x16x32_bf16 v[74:77], v[180:183], v[222:225], v[74:77]
	v_mfma_f32_16x16x32_bf16 v[70:73], v[188:191], v[222:225], 0
	v_mfma_f32_16x16x32_bf16 v[70:73], v[184:187], v[218:221], v[70:73]
	v_mfma_f32_16x16x32_bf16 v[86:89], v[184:187], v[210:213], 0
	v_mfma_f32_16x16x32_bf16 v[86:89], v[188:191], v[214:217], v[86:89]
	v_mfma_f32_16x16x32_bf16 v[90:93], v[180:183], v[214:217], 0
	v_mfma_f32_16x16x32_bf16 v[90:93], v[176:179], v[210:213], v[90:93]
	v_mfma_f32_16x16x32_bf16 v[106:109], v[176:179], v[202:205], 0
	v_mfma_f32_16x16x32_bf16 v[106:109], v[180:183], v[206:209], v[106:109]
	v_mfma_f32_16x16x32_bf16 v[102:105], v[188:191], v[206:209], 0
	v_mfma_f32_16x16x32_bf16 v[102:105], v[184:187], v[202:205], v[102:105]
	v_mfma_f32_16x16x32_bf16 v[118:121], v[184:187], v[194:197], 0
	v_mfma_f32_16x16x32_bf16 v[118:121], v[188:191], v[198:201], v[118:121]
	v_mfma_f32_16x16x32_bf16 v[122:125], v[180:183], v[198:201], 0
	v_mfma_f32_16x16x32_bf16 v[122:125], v[176:179], v[194:197], v[122:125]
	s_setprio 0
	s_barrier
	s_add_i32 s74, s64, s54
	v_lshl_add_u64 v[4:5], s[40:41], 0, v[134:135]
	s_mov_b32 m0, s74
	ds_read_b128 v[194:197], v154 offset:16384
	ds_read_b128 v[198:201], v154 offset:17408
	ds_read_b128 v[202:205], v154 offset:18432
	ds_read_b128 v[206:209], v154 offset:19456
	ds_read_b128 v[210:213], v154 offset:20480
	ds_read_b128 v[214:217], v154 offset:21504
	ds_read_b128 v[218:221], v154 offset:22528
	ds_read_b128 v[222:225], v154 offset:23552
	global_load_lds_dwordx4 v[4:5], off
	s_add_i32 m0, s74, 0x2000
	s_add_u32 s74, s40, 0xc0000
	v_lshl_add_u64 v[4:5], s[40:41], 0, v[136:137]
	s_addc_u32 s75, s41, 0
	s_add_i32 s76, s65, s54
	global_load_lds_dwordx4 v[4:5], off
	v_lshl_add_u64 v[4:5], s[74:75], 0, v[134:135]
	s_mov_b32 m0, s76
	s_nop 0
	global_load_lds_dwordx4 v[4:5], off
	v_lshl_add_u64 v[4:5], s[74:75], 0, v[136:137]
	s_add_i32 m0, s76, 0x2000
	s_nop 0
	global_load_lds_dwordx4 v[4:5], off
	v_lshl_add_u64 v[4:5], s[42:43], 0, v[134:135]
	s_mov_b32 m0, s55
	s_nop 0
	global_load_lds_dwordx4 v[4:5], off
	v_lshl_add_u64 v[4:5], s[42:43], 0, v[136:137]
	s_mov_b32 m0, s56
	s_nop 0
	global_load_lds_dwordx4 v[4:5], off
	s_waitcnt vmcnt(8)
	s_waitcnt lgkmcnt(0)
	s_barrier
; #define PG8_STAGE(bufoff, gbase, voff) do { _Pragma("unroll") for (int _i = 0; _i < 2; ++_i) \
;         __builtin_amdgcn_global_load_lds((const unsigned*)((const char*)(gbase) + (voff)[_i]), (PG8_LAS unsigned*)(lds + (bufoff) + ldsw + _i * 8192), 16, 0, 0); } while (0)
; #define PG8_LDA(dst, b, h) do { _Pragma("unroll") for (int m = 0; m < 4; ++m) _Pragma("unroll") for (int k = 0; k < 2; ++k) dst[m][k] = *(const PG8_LAS bf16x8*)(lds + PG8_SA(b, h) + aoff + m * 2048 + k * 1024); } while (0)
; #define PG8_LDB(dst, b, h) do { _Pragma("unroll") for (int n = 0; n < 2; ++n) _Pragma("unroll") for (int k = 0; k < 2; ++k) dst[n][k] = *(const PG8_LAS bf16x8*)(lds + PG8_SB(b, h) + boff + n * 2048 + k * 1024); } while (0)
; #define PG8_WAIT_V(n) asm volatile("s_waitcnt vmcnt(" #n ")" ::: "memory")
; #define PG8_WAIT_L(n) asm volatile("s_waitcnt lgkmcnt(" #n ")" ::: "memory")
; #define PG8_BAR __builtin_amdgcn_s_barrier()
; #define PG8_SCHED __builtin_amdgcn_sched_barrier(0)
; template <class Epi, class Sched, bool ALIGN_EPI = false, bool SP2 = false, bool RS = false, bool BPRE = false>
; __device__ __forceinline__ void gemm_phase(PG8_LAS unsigned char* lds, const Gemm g, const Sched& S, const Epi& E, const float* rs_ss = nullptr, PG8_LAS float* rs_tab = nullptr) {
;     ...
;             PG8_LDB(B0, 0, 0); PG8_LDB(B1, 0, 1); PG8_SCHED; PG8_LDA(At, 0, 0); PG8_STAGE(PG8_SA(1, 1), a1 + hstep, voffA);
;             PG8_WAIT_V(8); PG8_WAIT_L(0); PG8_BAR; PG8_MMA(0, 0, At, B0); PG8_MMA(0, 1, At, B1); PG8_BAR; PG8_SCHED;
;             PG8_LDA(At, 0, 1); PG8_STAGE(PG8_SB(0, 0), b2, voffB); PG8_STAGE(PG8_SB(0, 1), b2 + hstep, voffB); PG8_STAGE(PG8_SA(0, 0), a2, voffA);
;             PG8_WAIT_V(8); PG8_WAIT_L(0); PG8_BAR; PG8_MMA(1, 0, At, B0); PG8_MMA(1, 1, At, B1); PG8_BAR; PG8_SCHED;
;             PG8_LDB(B0, 1, 0); PG8_LDB(B1, 1, 1); PG8_SCHED; PG8_LDA(At, 1, 0); PG8_STAGE(PG8_SA(0, 1), a2 + hstep, voffA);
;             PG8_WAIT_V(8); PG8_WAIT_L(0); PG8_BAR; PG8_MMA(0, 0, At, B0); PG8_MMA(0, 1, At, B1); PG8_BAR; PG8_SCHED;
;             PG8_LDA(At, 1, 1); PG8_STAGE(PG8_SB(1, 0), b3, voffB); PG8_STAGE(PG8_SB(1, 1), b3 + hstep, voffB); PG8_STAGE(PG8_SA(1, 0), a3, voffA);
;             PG8_WAIT_V(8); PG8_WAIT_L(0); PG8_BAR; PG8_MMA(1, 0, At, B0); PG8_MMA(1, 1, At, B1); PG8_BAR; PG8_SCHED;
	s_setprio 1
	s_waitcnt lgkmcnt(0)
	v_mfma_f32_16x16x32_bf16 v[66:69], v[160:163], v[194:197], 0
	v_mfma_f32_16x16x32_bf16 v[66:69], v[164:167], v[198:201], v[66:69]
	v_mfma_f32_16x16x32_bf16 v[62:65], v[172:175], v[198:201], 0
	v_mfma_f32_16x16x32_bf16 v[62:65], v[168:171], v[194:197], v[62:65]
	v_mfma_f32_16x16x32_bf16 v[46:49], v[168:171], v[202:205], 0
	v_mfma_f32_16x16x32_bf16 v[46:49], v[172:175], v[206:209], v[46:49]
	v_mfma_f32_16x16x32_bf16 v[50:53], v[164:167], v[206:209], 0
	v_mfma_f32_16x16x32_bf16 v[50:53], v[160:163], v[202:205], v[50:53]
	v_mfma_f32_16x16x32_bf16 v[34:37], v[160:163], v[210:213], 0
	v_mfma_f32_16x16x32_bf16 v[34:37], v[164:167], v[214:217], v[34:37]
	v_mfma_f32_16x16x32_bf16 v[30:33], v[172:175], v[214:217], 0
	v_mfma_f32_16x16x32_bf16 v[30:33], v[168:171], v[210:213], v[30:33]
	v_mfma_f32_16x16x32_bf16 v[14:17], v[168:171], v[218:221], 0
	v_mfma_f32_16x16x32_bf16 v[14:17], v[172:175], v[222:225], v[14:17]
	v_mfma_f32_16x16x32_bf16 v[18:21], v[164:167], v[222:225], 0
	v_mfma_f32_16x16x32_bf16 v[18:21], v[160:163], v[218:221], v[18:21]
	s_setprio 0
	s_setprio 1
	v_mfma_f32_16x16x32_bf16 v[10:13], v[176:179], v[218:221], 0
	v_mfma_f32_16x16x32_bf16 v[10:13], v[180:183], v[222:225], v[10:13]
	v_mfma_f32_16x16x32_bf16 v[4:7], v[188:191], v[222:225], 0
	v_mfma_f32_16x16x32_bf16 v[4:7], v[184:187], v[218:221], v[4:7]
	v_mfma_f32_16x16x32_bf16 v[22:25], v[184:187], v[210:213], 0
	v_mfma_f32_16x16x32_bf16 v[22:25], v[188:191], v[214:217], v[22:25]
	v_mfma_f32_16x16x32_bf16 v[26:29], v[180:183], v[214:217], 0
	v_mfma_f32_16x16x32_bf16 v[26:29], v[176:179], v[210:213], v[26:29]
	v_mfma_f32_16x16x32_bf16 v[42:45], v[176:179], v[202:205], 0
	v_mfma_f32_16x16x32_bf16 v[42:45], v[180:183], v[206:209], v[42:45]
	v_mfma_f32_16x16x32_bf16 v[38:41], v[188:191], v[206:209], 0
	v_mfma_f32_16x16x32_bf16 v[38:41], v[184:187], v[202:205], v[38:41]
	v_mfma_f32_16x16x32_bf16 v[54:57], v[184:187], v[194:197], 0
	v_mfma_f32_16x16x32_bf16 v[54:57], v[188:191], v[198:201], v[54:57]
	v_mfma_f32_16x16x32_bf16 v[58:61], v[180:183], v[198:201], 0
	v_mfma_f32_16x16x32_bf16 v[58:61], v[176:179], v[194:197], v[58:61]
	s_setprio 0
	s_barrier
	s_add_i32 s74, 0, 0x18000
	v_add_u32_e32 v3, s74, v150
	s_add_i32 s75, 0, 0x1c000
	ds_read_b128 v[160:163], v3
	ds_read_b128 v[164:167], v3 offset:1024
	ds_read_b128 v[168:171], v3 offset:2048
	ds_read_b128 v[172:175], v3 offset:3072
	v_add_u32_e32 v3, s75, v150
	ds_read_b128 v[176:179], v3
	ds_read_b128 v[180:183], v3 offset:1024
	ds_read_b128 v[184:187], v3 offset:2048
	ds_read_b128 v[188:191], v3 offset:3072
	s_add_u32 s42, s42, 0xc0000
	s_addc_u32 s43, s43, 0
	s_mov_b32 m0, s57
	v_lshl_add_u64 v[8:9], s[42:43], 0, v[134:135]
	ds_read_b128 v[194:197], v154 offset:32768
	ds_read_b128 v[198:201], v154 offset:33792
	ds_read_b128 v[202:205], v154 offset:34816
	ds_read_b128 v[206:209], v154 offset:35840
	ds_read_b128 v[210:213], v154 offset:36864
	ds_read_b128 v[214:217], v154 offset:37888
	ds_read_b128 v[218:221], v154 offset:38912
	ds_read_b128 v[222:225], v154 offset:39936
	global_load_lds_dwordx4 v[8:9], off
	v_lshl_add_u64 v[8:9], s[42:43], 0, v[136:137]
	s_mov_b32 m0, s58
	s_nop 0
	global_load_lds_dwordx4 v[8:9], off
	s_waitcnt vmcnt(8)
	s_waitcnt lgkmcnt(0)
	s_barrier
	s_setprio 1
	s_waitcnt lgkmcnt(0)
	v_mfma_f32_16x16x32_bf16 v[130:133], v[160:163], v[194:197], v[130:133]
	v_mfma_f32_16x16x32_bf16 v[130:133], v[164:167], v[198:201], v[130:133]
	v_mfma_f32_16x16x32_bf16 v[126:129], v[172:175], v[198:201], v[126:129]
	v_mfma_f32_16x16x32_bf16 v[126:129], v[168:171], v[194:197], v[126:129]
	v_mfma_f32_16x16x32_bf16 v[110:113], v[168:171], v[202:205], v[110:113]
	v_mfma_f32_16x16x32_bf16 v[110:113], v[172:175], v[206:209], v[110:113]
	v_mfma_f32_16x16x32_bf16 v[114:117], v[164:167], v[206:209], v[114:117]
	v_mfma_f32_16x16x32_bf16 v[114:117], v[160:163], v[202:205], v[114:117]
	v_mfma_f32_16x16x32_bf16 v[98:101], v[160:163], v[210:213], v[98:101]
	v_mfma_f32_16x16x32_bf16 v[98:101], v[164:167], v[214:217], v[98:101]
	v_mfma_f32_16x16x32_bf16 v[94:97], v[172:175], v[214:217], v[94:97]
	v_mfma_f32_16x16x32_bf16 v[94:97], v[168:171], v[210:213], v[94:97]
	v_mfma_f32_16x16x32_bf16 v[78:81], v[168:171], v[218:221], v[78:81]
	v_mfma_f32_16x16x32_bf16 v[78:81], v[172:175], v[222:225], v[78:81]
	v_mfma_f32_16x16x32_bf16 v[82:85], v[164:167], v[222:225], v[82:85]
	v_mfma_f32_16x16x32_bf16 v[82:85], v[160:163], v[218:221], v[82:85]
	s_setprio 0
	s_setprio 1
	v_mfma_f32_16x16x32_bf16 v[74:77], v[176:179], v[218:221], v[74:77]
	v_mfma_f32_16x16x32_bf16 v[74:77], v[180:183], v[222:225], v[74:77]
	v_mfma_f32_16x16x32_bf16 v[70:73], v[188:191], v[222:225], v[70:73]
	v_mfma_f32_16x16x32_bf16 v[70:73], v[184:187], v[218:221], v[70:73]
	v_mfma_f32_16x16x32_bf16 v[86:89], v[184:187], v[210:213], v[86:89]
	v_mfma_f32_16x16x32_bf16 v[86:89], v[188:191], v[214:217], v[86:89]
	v_mfma_f32_16x16x32_bf16 v[90:93], v[180:183], v[214:217], v[90:93]
	v_mfma_f32_16x16x32_bf16 v[90:93], v[176:179], v[210:213], v[90:93]
	v_mfma_f32_16x16x32_bf16 v[106:109], v[176:179], v[202:205], v[106:109]
	v_mfma_f32_16x16x32_bf16 v[106:109], v[180:183], v[206:209], v[106:109]
	v_mfma_f32_16x16x32_bf16 v[102:105], v[188:191], v[206:209], v[102:105]
	v_mfma_f32_16x16x32_bf16 v[102:105], v[184:187], v[202:205], v[102:105]
	v_mfma_f32_16x16x32_bf16 v[118:121], v[184:187], v[194:197], v[118:121]
	v_mfma_f32_16x16x32_bf16 v[118:121], v[188:191], v[198:201], v[118:121]
	v_mfma_f32_16x16x32_bf16 v[122:125], v[180:183], v[198:201], v[122:125]
	v_mfma_f32_16x16x32_bf16 v[122:125], v[176:179], v[194:197], v[122:125]
	s_setprio 0
	s_barrier
; #define PG8_STAGE(bufoff, gbase, voff) do { _Pragma("unroll") for (int _i = 0; _i < 2; ++_i) \
;         __builtin_amdgcn_global_load_lds((const unsigned*)((const char*)(gbase) + (voff)[_i]), (PG8_LAS unsigned*)(lds + (bufoff) + ldsw + _i * 8192), 16, 0, 0); } while (0)
; #define PG8_LDA(dst, b, h) do { _Pragma("unroll") for (int m = 0; m < 4; ++m) _Pragma("unroll") for (int k = 0; k < 2; ++k) dst[m][k] = *(const PG8_LAS bf16x8*)(lds + PG8_SA(b, h) + aoff + m * 2048 + k * 1024); } while (0)
; #define PG8_LDB(dst, b, h) do { _Pragma("unroll") for (int n = 0; n < 2; ++n) _Pragma("unroll") for (int k = 0; k < 2; ++k) dst[n][k] = *(const PG8_LAS bf16x8*)(lds + PG8_SB(b, h) + boff + n * 2048 + k * 1024); } while (0)
; #define PG8_WAIT_V(n) asm volatile("s_waitcnt vmcnt(" #n ")" ::: "memory")
; #define PG8_WAIT_L(n) asm volatile("s_waitcnt lgkmcnt(" #n ")" ::: "memory")
; #define PG8_BAR __builtin_amdgcn_s_barrier()
; #define PG8_SCHED __builtin_amdgcn_sched_barrier(0)
; template <class Epi, class Sched, bool ALIGN_EPI = false, bool SP2 = false, bool RS = false, bool BPRE = false>
; __device__ __forceinline__ void gemm_phase(PG8_LAS unsigned char* lds, const Gemm g, const Sched& S, const Epi& E, const float* rs_ss = nullptr, PG8_LAS float* rs_tab = nullptr) {
;     ...
;             PG8_LDB(B0, 0, 0); PG8_LDB(B1, 0, 1); PG8_SCHED; PG8_LDA(At, 0, 0); PG8_STAGE(PG8_SA(1, 1), a1 + hstep, voffA);
;             PG8_WAIT_V(8); PG8_WAIT_L(0); PG8_BAR; PG8_MMA(0, 0, At, B0); PG8_MMA(0, 1, At, B1); PG8_BAR; PG8_SCHED;
;             PG8_LDA(At, 0, 1); PG8_STAGE(PG8_SB(0, 0), b2, voffB); PG8_STAGE(PG8_SB(0, 1), b2 + hstep, voffB); PG8_STAGE(PG8_SA(0, 0), a2, voffA);
;             PG8_WAIT_V(8); PG8_WAIT_L(0); PG8_BAR; PG8_MMA(1, 0, At, B0); PG8_MMA(1, 1, At, B1); PG8_BAR; PG8_SCHED;
;             PG8_LDB(B0, 1, 0); PG8_LDB(B1, 1, 1); PG8_SCHED; PG8_LDA(At, 1, 0); PG8_STAGE(PG8_SA(0, 1), a2 + hstep, voffA);
;             PG8_WAIT_V(8); PG8_WAIT_L(0); PG8_BAR; PG8_MMA(0, 0, At, B0); PG8_MMA(0, 1, At, B1); PG8_BAR; PG8_SCHED;
;             PG8_LDA(At, 1, 1); PG8_STAGE(PG8_SB(1, 0), b3, voffB); PG8_STAGE(PG8_SB(1, 1), b3 + hstep, voffB); PG8_STAGE(PG8_SA(1, 0), a3, voffA);
;             PG8_WAIT_V(8); PG8_WAIT_L(0); PG8_BAR; PG8_MMA(1, 0, At, B0); PG8_MMA(1, 1, At, B1); PG8_BAR; PG8_SCHED;
	s_add_u32 s42, s40, 0x4000
	s_addc_u32 s43, s41, 0
	s_add_i32 s74, s74, s54
	v_lshl_add_u64 v[8:9], s[42:43], 0, v[134:135]
	s_mov_b32 m0, s74
	ds_read_b128 v[194:197], v154 offset:49152
	ds_read_b128 v[198:201], v154 offset:50176
	ds_read_b128 v[202:205], v154 offset:51200
	ds_read_b128 v[206:209], v154 offset:52224
	ds_read_b128 v[210:213], v154 offset:53248
	ds_read_b128 v[214:217], v154 offset:54272
	ds_read_b128 v[218:221], v154 offset:55296
	ds_read_b128 v[222:225], v154 offset:56320
	global_load_lds_dwordx4 v[8:9], off
	s_add_i32 m0, s74, 0x2000
	s_add_u32 s40, s40, 0xc4000
	v_lshl_add_u64 v[8:9], s[42:43], 0, v[136:137]
	s_addc_u32 s41, s41, 0
	s_add_i32 s42, s75, s54
	global_load_lds_dwordx4 v[8:9], off
	v_lshl_add_u64 v[8:9], s[40:41], 0, v[134:135]
	s_mov_b32 m0, s42
	s_nop 0
	global_load_lds_dwordx4 v[8:9], off
	v_lshl_add_u64 v[8:9], s[40:41], 0, v[136:137]
	s_add_i32 m0, s42, 0x2000
	s_nop 0
	global_load_lds_dwordx4 v[8:9], off
	v_lshl_add_u64 v[8:9], s[38:39], 0, v[134:135]
	s_mov_b32 m0, s60
	s_nop 0
	global_load_lds_dwordx4 v[8:9], off
	v_lshl_add_u64 v[8:9], s[38:39], 0, v[136:137]
	s_mov_b32 m0, s61
	s_nop 0
	global_load_lds_dwordx4 v[8:9], off
	s_waitcnt vmcnt(8)
	s_waitcnt lgkmcnt(0)
	s_barrier
	s_setprio 1
	s_waitcnt lgkmcnt(0)
	v_mfma_f32_16x16x32_bf16 v[66:69], v[160:163], v[194:197], v[66:69]
	v_mfma_f32_16x16x32_bf16 v[66:69], v[164:167], v[198:201], v[66:69]
	v_mfma_f32_16x16x32_bf16 v[62:65], v[172:175], v[198:201], v[62:65]
	v_mfma_f32_16x16x32_bf16 v[62:65], v[168:171], v[194:197], v[62:65]
	v_mfma_f32_16x16x32_bf16 v[46:49], v[168:171], v[202:205], v[46:49]
	v_mfma_f32_16x16x32_bf16 v[46:49], v[172:175], v[206:209], v[46:49]
	v_mfma_f32_16x16x32_bf16 v[50:53], v[164:167], v[206:209], v[50:53]
	v_mfma_f32_16x16x32_bf16 v[50:53], v[160:163], v[202:205], v[50:53]
	v_mfma_f32_16x16x32_bf16 v[34:37], v[160:163], v[210:213], v[34:37]
	v_mfma_f32_16x16x32_bf16 v[34:37], v[164:167], v[214:217], v[34:37]
	v_mfma_f32_16x16x32_bf16 v[30:33], v[172:175], v[214:217], v[30:33]
	v_mfma_f32_16x16x32_bf16 v[30:33], v[168:171], v[210:213], v[30:33]
	v_mfma_f32_16x16x32_bf16 v[14:17], v[168:171], v[218:221], v[14:17]
	v_mfma_f32_16x16x32_bf16 v[14:17], v[172:175], v[222:225], v[14:17]
	v_mfma_f32_16x16x32_bf16 v[18:21], v[164:167], v[222:225], v[18:21]
	v_mfma_f32_16x16x32_bf16 v[18:21], v[160:163], v[218:221], v[18:21]
	s_setprio 0
	s_setprio 1
	v_mfma_f32_16x16x32_bf16 v[58:61], v[176:179], v[194:197], v[58:61]
	v_mfma_f32_16x16x32_bf16 v[58:61], v[180:183], v[198:201], v[58:61]
	v_mfma_f32_16x16x32_bf16 v[54:57], v[188:191], v[198:201], v[54:57]
	v_mfma_f32_16x16x32_bf16 v[54:57], v[184:187], v[194:197], v[54:57]
	v_mfma_f32_16x16x32_bf16 v[38:41], v[184:187], v[202:205], v[38:41]
	v_mfma_f32_16x16x32_bf16 v[38:41], v[188:191], v[206:209], v[38:41]
	v_mfma_f32_16x16x32_bf16 v[42:45], v[180:183], v[206:209], v[42:45]
	v_mfma_f32_16x16x32_bf16 v[42:45], v[176:179], v[202:205], v[42:45]
	v_mfma_f32_16x16x32_bf16 v[26:29], v[176:179], v[210:213], v[26:29]
	v_mfma_f32_16x16x32_bf16 v[26:29], v[180:183], v[214:217], v[26:29]
	v_mfma_f32_16x16x32_bf16 v[22:25], v[188:191], v[214:217], v[22:25]
	v_mfma_f32_16x16x32_bf16 v[22:25], v[184:187], v[210:213], v[22:25]
	v_mfma_f32_16x16x32_bf16 v[8:11], v[176:179], v[218:221], v[10:13]
	v_mfma_f32_16x16x32_bf16 v[10:13], v[180:183], v[222:225], v[8:11]
	v_mfma_f32_16x16x32_bf16 v[4:7], v[188:191], v[222:225], v[4:7]
	v_mfma_f32_16x16x32_bf16 v[6:9], v[184:187], v[218:221], v[4:7]
	s_setprio 0
	s_barrier
	s_add_i32 s38, s73, 2
	s_add_u32 s6, s6, 0x8000
	s_addc_u32 s7, s7, 0
	s_cmp_gt_u32 s73, 45
	s_mov_b32 s73, s38
	s_branch .LBB0_753
.LBB0_752:
	s_add_u32 s38, s10, s6
	v_add_u32_e32 v3, s64, v150
	s_addc_u32 s39, s11, s7
	ds_read_b128 v[160:163], v3
	ds_read_b128 v[164:167], v3 offset:1024
	ds_read_b128 v[168:171], v3 offset:2048
	ds_read_b128 v[172:175], v3 offset:3072
	v_add_u32_e32 v3, s65, v150
	s_add_u32 s38, s38, 0x8000
	ds_read_b128 v[176:179], v3
	ds_read_b128 v[180:183], v3 offset:1024
	ds_read_b128 v[184:187], v3 offset:2048
	ds_read_b128 v[188:191], v3 offset:3072
	s_addc_u32 s39, s39, 0
	s_add_u32 s40, s71, s6
	s_addc_u32 s41, s72, s7
	s_cmp_eq_u32 s6, 0xb8000
	s_cselect_b32 s42, s20, s38
	s_cselect_b32 s43, s21, s39
	s_cselect_b32 s40, s36, s40
	s_cselect_b32 s41, s37, s41
	s_add_u32 s38, s42, 0x4000
	s_addc_u32 s39, s43, 0
	v_lshl_add_u64 v[4:5], v[146:147], 0, s[6:7]
	s_add_i32 m0, s55, 0xc000
	ds_read_b128 v[194:197], v154
	ds_read_b128 v[198:201], v154 offset:1024
	ds_read_b128 v[202:205], v154 offset:2048
	ds_read_b128 v[206:209], v154 offset:3072
	ds_read_b128 v[210:213], v154 offset:4096
	ds_read_b128 v[214:217], v154 offset:5120
	ds_read_b128 v[218:221], v154 offset:6144
	ds_read_b128 v[222:225], v154 offset:7168
	global_load_lds_dwordx4 v[4:5], off
	v_lshl_add_u64 v[4:5], v[148:149], 0, s[6:7]
	s_add_i32 m0, s55, 0xe000
	s_nop 0
	global_load_lds_dwordx4 v[4:5], off
	s_waitcnt vmcnt(8)
	s_waitcnt lgkmcnt(0)
	s_barrier
; #define PG8_STAGE(bufoff, gbase, voff) do { _Pragma("unroll") for (int _i = 0; _i < 2; ++_i) \
;         __builtin_amdgcn_global_load_lds((const unsigned*)((const char*)(gbase) + (voff)[_i]), (PG8_LAS unsigned*)(lds + (bufoff) + ldsw + _i * 8192), 16, 0, 0); } while (0)
; #define PG8_LDA(dst, b, h) do { _Pragma("unroll") for (int m = 0; m < 4; ++m) _Pragma("unroll") for (int k = 0; k < 2; ++k) dst[m][k] = *(const PG8_LAS bf16x8*)(lds + PG8_SA(b, h) + aoff + m * 2048 + k * 1024); } while (0)
; #define PG8_MMA(ai, bj, At, Bt) do { __builtin_amdgcn_s_setprio(1); _Pragma("unroll") for (int m = 0; m < 4; ++m) _Pragma("unroll") for (int n = 0; n < 2; ++n) _Pragma("unroll") for (int k = 0; k < 2; ++k) \
;         acc[ai][bj][m][n] = __builtin_amdgcn_mfma_f32_16x16x32_bf16(Bt[n][k], At[m][k], acc[ai][bj][m][n], 0, 0, 0); __builtin_amdgcn_s_setprio(0); } while (0)
; #define PG8_WAIT_V(n) asm volatile("s_waitcnt vmcnt(" #n ")" ::: "memory")
; #define PG8_WAIT_L(n) asm volatile("s_waitcnt lgkmcnt(" #n ")" ::: "memory")
; #define PG8_BAR __builtin_amdgcn_s_barrier()
; #define PG8_SCHED __builtin_amdgcn_sched_barrier(0)
; template <class Epi, class Sched, bool ALIGN_EPI = false, bool SP2 = false, bool RS = false, bool BPRE = false>
; __device__ __forceinline__ void gemm_phase(PG8_LAS unsigned char* lds, const Gemm g, const Sched& S, const Epi& E, const float* rs_ss = nullptr, PG8_LAS float* rs_tab = nullptr) {
;     ...
;             PG8_WAIT_V(8); PG8_WAIT_L(0); PG8_BAR; PG8_MMA(0, 0, At, B0); PG8_MMA(0, 1, At, B1); PG8_BAR; PG8_SCHED;
;             PG8_LDA(At, 0, 1); PG8_STAGE(PG8_SB(0, 0), b2, voffB); PG8_STAGE(PG8_SB(0, 1), b2 + hstep, voffB); PG8_STAGE(PG8_SA(0, 0), a2, voffA);
;             PG8_WAIT_V(8); PG8_WAIT_L(0); PG8_BAR; PG8_MMA(1, 0, At, B0); PG8_MMA(1, 1, At, B1); PG8_BAR; PG8_SCHED;
	s_setprio 1
	s_waitcnt lgkmcnt(0)
	v_mfma_f32_16x16x32_bf16 v[130:133], v[160:163], v[194:197], v[130:133]
	v_mfma_f32_16x16x32_bf16 v[130:133], v[164:167], v[198:201], v[130:133]
	v_mfma_f32_16x16x32_bf16 v[126:129], v[172:175], v[198:201], v[126:129]
	v_mfma_f32_16x16x32_bf16 v[126:129], v[168:171], v[194:197], v[126:129]
	v_mfma_f32_16x16x32_bf16 v[110:113], v[168:171], v[202:205], v[110:113]
	v_mfma_f32_16x16x32_bf16 v[110:113], v[172:175], v[206:209], v[110:113]
	v_mfma_f32_16x16x32_bf16 v[114:117], v[164:167], v[206:209], v[114:117]
	v_mfma_f32_16x16x32_bf16 v[114:117], v[160:163], v[202:205], v[114:117]
	v_mfma_f32_16x16x32_bf16 v[98:101], v[160:163], v[210:213], v[98:101]
	v_mfma_f32_16x16x32_bf16 v[98:101], v[164:167], v[214:217], v[98:101]
	v_mfma_f32_16x16x32_bf16 v[94:97], v[172:175], v[214:217], v[94:97]
	v_mfma_f32_16x16x32_bf16 v[94:97], v[168:171], v[210:213], v[94:97]
	v_mfma_f32_16x16x32_bf16 v[78:81], v[168:171], v[218:221], v[78:81]
	v_mfma_f32_16x16x32_bf16 v[78:81], v[172:175], v[222:225], v[78:81]
	v_mfma_f32_16x16x32_bf16 v[82:85], v[164:167], v[222:225], v[82:85]
	v_mfma_f32_16x16x32_bf16 v[82:85], v[160:163], v[218:221], v[82:85]
	s_setprio 0
	s_setprio 1
	v_mfma_f32_16x16x32_bf16 v[74:77], v[176:179], v[218:221], v[74:77]
	v_mfma_f32_16x16x32_bf16 v[74:77], v[180:183], v[222:225], v[74:77]
	v_mfma_f32_16x16x32_bf16 v[70:73], v[188:191], v[222:225], v[70:73]
	v_mfma_f32_16x16x32_bf16 v[70:73], v[184:187], v[218:221], v[70:73]
	v_mfma_f32_16x16x32_bf16 v[86:89], v[184:187], v[210:213], v[86:89]
	v_mfma_f32_16x16x32_bf16 v[86:89], v[188:191], v[214:217], v[86:89]
	v_mfma_f32_16x16x32_bf16 v[90:93], v[180:183], v[214:217], v[90:93]
	v_mfma_f32_16x16x32_bf16 v[90:93], v[176:179], v[210:213], v[90:93]
	v_mfma_f32_16x16x32_bf16 v[106:109], v[176:179], v[202:205], v[106:109]
	v_mfma_f32_16x16x32_bf16 v[106:109], v[180:183], v[206:209], v[106:109]
	v_mfma_f32_16x16x32_bf16 v[102:105], v[188:191], v[206:209], v[102:105]
	v_mfma_f32_16x16x32_bf16 v[102:105], v[184:187], v[202:205], v[102:105]
	v_mfma_f32_16x16x32_bf16 v[118:121], v[184:187], v[194:197], v[118:121]
	v_mfma_f32_16x16x32_bf16 v[118:121], v[188:191], v[198:201], v[118:121]
	v_mfma_f32_16x16x32_bf16 v[122:125], v[180:183], v[198:201], v[122:125]
	v_mfma_f32_16x16x32_bf16 v[122:125], v[176:179], v[194:197], v[122:125]
	s_setprio 0
	s_barrier
	s_add_i32 s74, s64, s54
	v_lshl_add_u64 v[4:5], s[40:41], 0, v[134:135]
	s_mov_b32 m0, s74
	ds_read_b128 v[194:197], v154 offset:16384
	ds_read_b128 v[198:201], v154 offset:17408
	ds_read_b128 v[202:205], v154 offset:18432
	ds_read_b128 v[206:209], v154 offset:19456
	ds_read_b128 v[210:213], v154 offset:20480
	ds_read_b128 v[214:217], v154 offset:21504
	ds_read_b128 v[218:221], v154 offset:22528
	ds_read_b128 v[222:225], v154 offset:23552
	global_load_lds_dwordx4 v[4:5], off
	s_add_i32 m0, s74, 0x2000
	s_add_u32 s74, s40, 0xc0000
	v_lshl_add_u64 v[4:5], s[40:41], 0, v[136:137]
	s_addc_u32 s75, s41, 0
	s_add_i32 s76, s65, s54
	global_load_lds_dwordx4 v[4:5], off
	v_lshl_add_u64 v[4:5], s[74:75], 0, v[134:135]
	s_mov_b32 m0, s76
	s_nop 0
	global_load_lds_dwordx4 v[4:5], off
	v_lshl_add_u64 v[4:5], s[74:75], 0, v[136:137]
	s_add_i32 m0, s76, 0x2000
	s_nop 0
	global_load_lds_dwordx4 v[4:5], off
	v_lshl_add_u64 v[4:5], s[42:43], 0, v[134:135]
	s_mov_b32 m0, s55
	s_nop 0
	global_load_lds_dwordx4 v[4:5], off
	v_lshl_add_u64 v[4:5], s[42:43], 0, v[136:137]
	s_mov_b32 m0, s56
	s_nop 0
	global_load_lds_dwordx4 v[4:5], off
	s_waitcnt vmcnt(8)
	s_waitcnt lgkmcnt(0)
	s_barrier
	s_setprio 1
	s_waitcnt lgkmcnt(0)
	v_mfma_f32_16x16x32_bf16 v[66:69], v[160:163], v[194:197], v[66:69]
	v_mfma_f32_16x16x32_bf16 v[66:69], v[164:167], v[198:201], v[66:69]
	v_mfma_f32_16x16x32_bf16 v[62:65], v[172:175], v[198:201], v[62:65]
	v_mfma_f32_16x16x32_bf16 v[62:65], v[168:171], v[194:197], v[62:65]
	v_mfma_f32_16x16x32_bf16 v[46:49], v[168:171], v[202:205], v[46:49]
	v_mfma_f32_16x16x32_bf16 v[46:49], v[172:175], v[206:209], v[46:49]
	v_mfma_f32_16x16x32_bf16 v[50:53], v[164:167], v[206:209], v[50:53]
	v_mfma_f32_16x16x32_bf16 v[50:53], v[160:163], v[202:205], v[50:53]
	v_mfma_f32_16x16x32_bf16 v[34:37], v[160:163], v[210:213], v[34:37]
	v_mfma_f32_16x16x32_bf16 v[34:37], v[164:167], v[214:217], v[34:37]
	v_mfma_f32_16x16x32_bf16 v[30:33], v[172:175], v[214:217], v[30:33]
	v_mfma_f32_16x16x32_bf16 v[30:33], v[168:171], v[210:213], v[30:33]
	v_mfma_f32_16x16x32_bf16 v[14:17], v[168:171], v[218:221], v[14:17]
	v_mfma_f32_16x16x32_bf16 v[14:17], v[172:175], v[222:225], v[14:17]
	v_mfma_f32_16x16x32_bf16 v[18:21], v[164:167], v[222:225], v[18:21]
	v_mfma_f32_16x16x32_bf16 v[18:21], v[160:163], v[218:221], v[18:21]
	s_setprio 0
	s_setprio 1
	v_mfma_f32_16x16x32_bf16 v[10:13], v[176:179], v[218:221], v[10:13]
	v_mfma_f32_16x16x32_bf16 v[10:13], v[180:183], v[222:225], v[10:13]
	v_mfma_f32_16x16x32_bf16 v[4:7], v[188:191], v[222:225], v[6:9]
	v_mfma_f32_16x16x32_bf16 v[4:7], v[184:187], v[218:221], v[4:7]
	v_mfma_f32_16x16x32_bf16 v[22:25], v[184:187], v[210:213], v[22:25]
	v_mfma_f32_16x16x32_bf16 v[22:25], v[188:191], v[214:217], v[22:25]
	v_mfma_f32_16x16x32_bf16 v[26:29], v[180:183], v[214:217], v[26:29]
	v_mfma_f32_16x16x32_bf16 v[26:29], v[176:179], v[210:213], v[26:29]
	v_mfma_f32_16x16x32_bf16 v[42:45], v[176:179], v[202:205], v[42:45]
	v_mfma_f32_16x16x32_bf16 v[42:45], v[180:183], v[206:209], v[42:45]
	v_mfma_f32_16x16x32_bf16 v[38:41], v[188:191], v[206:209], v[38:41]
	v_mfma_f32_16x16x32_bf16 v[38:41], v[184:187], v[202:205], v[38:41]
	v_mfma_f32_16x16x32_bf16 v[54:57], v[184:187], v[194:197], v[54:57]
	v_mfma_f32_16x16x32_bf16 v[54:57], v[188:191], v[198:201], v[54:57]
	v_mfma_f32_16x16x32_bf16 v[58:61], v[180:183], v[198:201], v[58:61]
	v_mfma_f32_16x16x32_bf16 v[58:61], v[176:179], v[194:197], v[58:61]
	s_setprio 0
	s_barrier
; #define PG8_STAGE(bufoff, gbase, voff) do { _Pragma("unroll") for (int _i = 0; _i < 2; ++_i) \
;         __builtin_amdgcn_global_load_lds((const unsigned*)((const char*)(gbase) + (voff)[_i]), (PG8_LAS unsigned*)(lds + (bufoff) + ldsw + _i * 8192), 16, 0, 0); } while (0)
; #define PG8_LDA(dst, b, h) do { _Pragma("unroll") for (int m = 0; m < 4; ++m) _Pragma("unroll") for (int k = 0; k < 2; ++k) dst[m][k] = *(const PG8_LAS bf16x8*)(lds + PG8_SA(b, h) + aoff + m * 2048 + k * 1024); } while (0)
; #define PG8_LDB(dst, b, h) do { _Pragma("unroll") for (int n = 0; n < 2; ++n) _Pragma("unroll") for (int k = 0; k < 2; ++k) dst[n][k] = *(const PG8_LAS bf16x8*)(lds + PG8_SB(b, h) + boff + n * 2048 + k * 1024); } while (0)
; #define PG8_MMA(ai, bj, At, Bt) do { __builtin_amdgcn_s_setprio(1); _Pragma("unroll") for (int m = 0; m < 4; ++m) _Pragma("unroll") for (int n = 0; n < 2; ++n) _Pragma("unroll") for (int k = 0; k < 2; ++k) \
;         acc[ai][bj][m][n] = __builtin_amdgcn_mfma_f32_16x16x32_bf16(Bt[n][k], At[m][k], acc[ai][bj][m][n], 0, 0, 0); __builtin_amdgcn_s_setprio(0); } while (0)
; #define PG8_WAIT_V(n) asm volatile("s_waitcnt vmcnt(" #n ")" ::: "memory")
; #define PG8_WAIT_L(n) asm volatile("s_waitcnt lgkmcnt(" #n ")" ::: "memory")
; #define PG8_BAR __builtin_amdgcn_s_barrier()
; #define PG8_SCHED __builtin_amdgcn_sched_barrier(0)
; template <class Epi, class Sched, bool ALIGN_EPI = false, bool SP2 = false, bool RS = false, bool BPRE = false>
; __device__ __forceinline__ void gemm_phase(PG8_LAS unsigned char* lds, const Gemm g, const Sched& S, const Epi& E, const float* rs_ss = nullptr, PG8_LAS float* rs_tab = nullptr) {
;     ...
;             PG8_LDB(B0, 1, 0); PG8_LDB(B1, 1, 1); PG8_SCHED; PG8_LDA(At, 1, 0); PG8_STAGE(PG8_SA(0, 1), a2 + hstep, voffA);
;             PG8_WAIT_V(8); PG8_WAIT_L(0); PG8_BAR; PG8_MMA(0, 0, At, B0); PG8_MMA(0, 1, At, B1); PG8_BAR; PG8_SCHED;
	s_add_i32 s74, 0, 0x18000
	v_add_u32_e32 v3, s74, v150
	s_add_i32 s75, 0, 0x1c000
	ds_read_b128 v[160:163], v3
	ds_read_b128 v[164:167], v3 offset:1024
	ds_read_b128 v[168:171], v3 offset:2048
	ds_read_b128 v[172:175], v3 offset:3072
	v_add_u32_e32 v3, s75, v150
	ds_read_b128 v[176:179], v3
	ds_read_b128 v[180:183], v3 offset:1024
	ds_read_b128 v[184:187], v3 offset:2048
	ds_read_b128 v[188:191], v3 offset:3072
	s_add_u32 s42, s42, 0xc0000
	s_addc_u32 s43, s43, 0
	s_mov_b32 m0, s57
	v_lshl_add_u64 v[8:9], s[42:43], 0, v[134:135]
	ds_read_b128 v[194:197], v154 offset:32768
	ds_read_b128 v[198:201], v154 offset:33792
	ds_read_b128 v[202:205], v154 offset:34816
	ds_read_b128 v[206:209], v154 offset:35840
	ds_read_b128 v[210:213], v154 offset:36864
	ds_read_b128 v[214:217], v154 offset:37888
	ds_read_b128 v[218:221], v154 offset:38912
	ds_read_b128 v[222:225], v154 offset:39936
	global_load_lds_dwordx4 v[8:9], off
	v_lshl_add_u64 v[8:9], s[42:43], 0, v[136:137]
	s_mov_b32 m0, s58
	s_nop 0
	global_load_lds_dwordx4 v[8:9], off
	s_waitcnt vmcnt(8)
	s_waitcnt lgkmcnt(0)
	s_barrier
	s_setprio 1
	s_waitcnt lgkmcnt(0)
	v_mfma_f32_16x16x32_bf16 v[130:133], v[160:163], v[194:197], v[130:133]
	v_mfma_f32_16x16x32_bf16 v[130:133], v[164:167], v[198:201], v[130:133]
	v_mfma_f32_16x16x32_bf16 v[126:129], v[172:175], v[198:201], v[126:129]
	v_mfma_f32_16x16x32_bf16 v[126:129], v[168:171], v[194:197], v[126:129]
	v_mfma_f32_16x16x32_bf16 v[110:113], v[168:171], v[202:205], v[110:113]
	v_mfma_f32_16x16x32_bf16 v[110:113], v[172:175], v[206:209], v[110:113]
	v_mfma_f32_16x16x32_bf16 v[114:117], v[164:167], v[206:209], v[114:117]
	v_mfma_f32_16x16x32_bf16 v[114:117], v[160:163], v[202:205], v[114:117]
	v_mfma_f32_16x16x32_bf16 v[98:101], v[160:163], v[210:213], v[98:101]
	v_mfma_f32_16x16x32_bf16 v[98:101], v[164:167], v[214:217], v[98:101]
	v_mfma_f32_16x16x32_bf16 v[94:97], v[172:175], v[214:217], v[94:97]
	v_mfma_f32_16x16x32_bf16 v[94:97], v[168:171], v[210:213], v[94:97]
	v_mfma_f32_16x16x32_bf16 v[78:81], v[168:171], v[218:221], v[78:81]
	v_mfma_f32_16x16x32_bf16 v[78:81], v[172:175], v[222:225], v[78:81]
	v_mfma_f32_16x16x32_bf16 v[82:85], v[164:167], v[222:225], v[82:85]
	v_mfma_f32_16x16x32_bf16 v[82:85], v[160:163], v[218:221], v[82:85]
	s_setprio 0
	s_setprio 1
	v_mfma_f32_16x16x32_bf16 v[74:77], v[176:179], v[218:221], v[74:77]
	v_mfma_f32_16x16x32_bf16 v[74:77], v[180:183], v[222:225], v[74:77]
	v_mfma_f32_16x16x32_bf16 v[70:73], v[188:191], v[222:225], v[70:73]
	v_mfma_f32_16x16x32_bf16 v[70:73], v[184:187], v[218:221], v[70:73]
	v_mfma_f32_16x16x32_bf16 v[86:89], v[184:187], v[210:213], v[86:89]
	v_mfma_f32_16x16x32_bf16 v[86:89], v[188:191], v[214:217], v[86:89]
	v_mfma_f32_16x16x32_bf16 v[90:93], v[180:183], v[214:217], v[90:93]
	v_mfma_f32_16x16x32_bf16 v[90:93], v[176:179], v[210:213], v[90:93]
	v_mfma_f32_16x16x32_bf16 v[106:109], v[176:179], v[202:205], v[106:109]
	v_mfma_f32_16x16x32_bf16 v[106:109], v[180:183], v[206:209], v[106:109]
	v_mfma_f32_16x16x32_bf16 v[102:105], v[188:191], v[206:209], v[102:105]
	v_mfma_f32_16x16x32_bf16 v[102:105], v[184:187], v[202:205], v[102:105]
	v_mfma_f32_16x16x32_bf16 v[118:121], v[184:187], v[194:197], v[118:121]
	v_mfma_f32_16x16x32_bf16 v[118:121], v[188:191], v[198:201], v[118:121]
	v_mfma_f32_16x16x32_bf16 v[122:125], v[180:183], v[198:201], v[122:125]
	v_mfma_f32_16x16x32_bf16 v[122:125], v[176:179], v[194:197], v[122:125]
	s_setprio 0
	s_barrier
; #define PG8_STAGE(bufoff, gbase, voff) do { _Pragma("unroll") for (int _i = 0; _i < 2; ++_i) \
;         __builtin_amdgcn_global_load_lds((const unsigned*)((const char*)(gbase) + (voff)[_i]), (PG8_LAS unsigned*)(lds + (bufoff) + ldsw + _i * 8192), 16, 0, 0); } while (0)
; #define PG8_LDA(dst, b, h) do { _Pragma("unroll") for (int m = 0; m < 4; ++m) _Pragma("unroll") for (int k = 0; k < 2; ++k) dst[m][k] = *(const PG8_LAS bf16x8*)(lds + PG8_SA(b, h) + aoff + m * 2048 + k * 1024); } while (0)
; #define PG8_MMA(ai, bj, At, Bt) do { __builtin_amdgcn_s_setprio(1); _Pragma("unroll") for (int m = 0; m < 4; ++m) _Pragma("unroll") for (int n = 0; n < 2; ++n) _Pragma("unroll") for (int k = 0; k < 2; ++k) \
;         acc[ai][bj][m][n] = __builtin_amdgcn_mfma_f32_16x16x32_bf16(Bt[n][k], At[m][k], acc[ai][bj][m][n], 0, 0, 0); __builtin_amdgcn_s_setprio(0); } while (0)
; #define PG8_WAIT_V(n) asm volatile("s_waitcnt vmcnt(" #n ")" ::: "memory")
; #define PG8_WAIT_L(n) asm volatile("s_waitcnt lgkmcnt(" #n ")" ::: "memory")
; #define PG8_BAR __builtin_amdgcn_s_barrier()
; #define PG8_SCHED __builtin_amdgcn_sched_barrier(0)
; template <class Epi, class Sched, bool ALIGN_EPI = false, bool SP2 = false, bool RS = false, bool BPRE = false>
; __device__ __forceinline__ void gemm_phase(PG8_LAS unsigned char* lds, const Gemm g, const Sched& S, const Epi& E, const float* rs_ss = nullptr, PG8_LAS float* rs_tab = nullptr) {
;     ...
;             PG8_LDA(At, 1, 1); PG8_STAGE(PG8_SB(1, 0), b3, voffB); PG8_STAGE(PG8_SB(1, 1), b3 + hstep, voffB); PG8_STAGE(PG8_SA(1, 0), a3, voffA);
;             PG8_WAIT_V(8); PG8_WAIT_L(0); PG8_BAR; PG8_MMA(1, 0, At, B0); PG8_MMA(1, 1, At, B1); PG8_BAR; PG8_SCHED;
	s_add_u32 s42, s40, 0x4000
	s_addc_u32 s43, s41, 0
	s_add_i32 s74, s74, s54
	v_lshl_add_u64 v[8:9], s[42:43], 0, v[134:135]
	s_mov_b32 m0, s74
	ds_read_b128 v[194:197], v154 offset:49152
	ds_read_b128 v[198:201], v154 offset:50176
	ds_read_b128 v[202:205], v154 offset:51200
	ds_read_b128 v[206:209], v154 offset:52224
	ds_read_b128 v[210:213], v154 offset:53248
	ds_read_b128 v[214:217], v154 offset:54272
	ds_read_b128 v[218:221], v154 offset:55296
	ds_read_b128 v[222:225], v154 offset:56320
	global_load_lds_dwordx4 v[8:9], off
	s_add_i32 m0, s74, 0x2000
	s_add_u32 s40, s40, 0xc4000
	v_lshl_add_u64 v[8:9], s[42:43], 0, v[136:137]
	s_addc_u32 s41, s41, 0
	s_add_i32 s42, s75, s54
	global_load_lds_dwordx4 v[8:9], off
	v_lshl_add_u64 v[8:9], s[40:41], 0, v[134:135]
	s_mov_b32 m0, s42
	s_nop 0
	global_load_lds_dwordx4 v[8:9], off
	v_lshl_add_u64 v[8:9], s[40:41], 0, v[136:137]
	s_add_i32 m0, s42, 0x2000
	s_nop 0
	global_load_lds_dwordx4 v[8:9], off
	v_lshl_add_u64 v[8:9], s[38:39], 0, v[134:135]
	s_mov_b32 m0, s60
	s_nop 0
	global_load_lds_dwordx4 v[8:9], off
	v_lshl_add_u64 v[8:9], s[38:39], 0, v[136:137]
	s_mov_b32 m0, s61
	s_nop 0
	global_load_lds_dwordx4 v[8:9], off
	s_waitcnt vmcnt(8)
	s_waitcnt lgkmcnt(0)
	s_barrier
	s_setprio 1
	s_waitcnt lgkmcnt(0)
	v_mfma_f32_16x16x32_bf16 v[66:69], v[160:163], v[194:197], v[66:69]
	v_mfma_f32_16x16x32_bf16 v[66:69], v[164:167], v[198:201], v[66:69]
	v_mfma_f32_16x16x32_bf16 v[62:65], v[172:175], v[198:201], v[62:65]
	v_mfma_f32_16x16x32_bf16 v[62:65], v[168:171], v[194:197], v[62:65]
	v_mfma_f32_16x16x32_bf16 v[46:49], v[168:171], v[202:205], v[46:49]
	v_mfma_f32_16x16x32_bf16 v[46:49], v[172:175], v[206:209], v[46:49]
	v_mfma_f32_16x16x32_bf16 v[50:53], v[164:167], v[206:209], v[50:53]
	v_mfma_f32_16x16x32_bf16 v[50:53], v[160:163], v[202:205], v[50:53]
	v_mfma_f32_16x16x32_bf16 v[34:37], v[160:163], v[210:213], v[34:37]
	v_mfma_f32_16x16x32_bf16 v[34:37], v[164:167], v[214:217], v[34:37]
	v_mfma_f32_16x16x32_bf16 v[30:33], v[172:175], v[214:217], v[30:33]
	v_mfma_f32_16x16x32_bf16 v[30:33], v[168:171], v[210:213], v[30:33]
	v_mfma_f32_16x16x32_bf16 v[14:17], v[168:171], v[218:221], v[14:17]
	v_mfma_f32_16x16x32_bf16 v[14:17], v[172:175], v[222:225], v[14:17]
	v_mfma_f32_16x16x32_bf16 v[18:21], v[164:167], v[222:225], v[18:21]
	v_mfma_f32_16x16x32_bf16 v[18:21], v[160:163], v[218:221], v[18:21]
	s_setprio 0
	s_setprio 1
	v_mfma_f32_16x16x32_bf16 v[58:61], v[176:179], v[194:197], v[58:61]
	v_mfma_f32_16x16x32_bf16 v[58:61], v[180:183], v[198:201], v[58:61]
	v_mfma_f32_16x16x32_bf16 v[54:57], v[188:191], v[198:201], v[54:57]
	v_mfma_f32_16x16x32_bf16 v[54:57], v[184:187], v[194:197], v[54:57]
	v_mfma_f32_16x16x32_bf16 v[38:41], v[184:187], v[202:205], v[38:41]
	v_mfma_f32_16x16x32_bf16 v[38:41], v[188:191], v[206:209], v[38:41]
	v_mfma_f32_16x16x32_bf16 v[42:45], v[180:183], v[206:209], v[42:45]
	v_mfma_f32_16x16x32_bf16 v[42:45], v[176:179], v[202:205], v[42:45]
	v_mfma_f32_16x16x32_bf16 v[26:29], v[176:179], v[210:213], v[26:29]
	v_mfma_f32_16x16x32_bf16 v[26:29], v[180:183], v[214:217], v[26:29]
	v_mfma_f32_16x16x32_bf16 v[22:25], v[188:191], v[214:217], v[22:25]
	v_mfma_f32_16x16x32_bf16 v[22:25], v[184:187], v[210:213], v[22:25]
	v_mfma_f32_16x16x32_bf16 v[8:11], v[176:179], v[218:221], v[10:13]
	v_mfma_f32_16x16x32_bf16 v[10:13], v[180:183], v[222:225], v[8:11]
	v_mfma_f32_16x16x32_bf16 v[4:7], v[188:191], v[222:225], v[4:7]
	v_mfma_f32_16x16x32_bf16 v[6:9], v[184:187], v[218:221], v[4:7]
	s_setprio 0
	s_barrier
	s_add_i32 s38, s73, 2
	s_add_u32 s6, s6, 0x8000
	s_addc_u32 s7, s7, 0
	s_cmp_gt_u32 s73, 45
	s_mov_b32 s73, s38
	s_cbranch_scc1 .LBB0_759
